# prep: software-pipelined the triangular-inverse update loop (20 LDS reads in flight, counted lgkmcnt waits, plain v_fma)
# speedup vs baseline: 1.0641x; 1.0295x over previous
; __device__ void prep_unit(unsigned char* lds, int bh, int n, const bf16_t* pc, const float* scal, const float* convw  , float alog, float dtb, unsigned char* unit, float* egl, unsigned* flag, unsigned fval) {
;     ...
;             for (int j4 = 0; j4 < 4 * rb; ++j4) {
;                 const float t0 = Am[(4 * j4 + 0) * 68 + c], t1 = Am[(4 * j4 + 1) * 68 + c], t2 = Am[(4 * j4 + 2) * 68 + c], t3 = Am[(4 * j4 + 3) * 68 + c];
;                 const f32x2v T0 = {t0, t0}, T1 = {t1, t1}, T2 = {t2, t2}, T3 = {t3, t3};
; #pragma unroll
;                 for (int q = 0; q < 8; ++q) { const f32x4 a4 = *(const f32x4*)(AmV + (16 * rb + 2 * q) * 68 + 4 * j4), b4 = *(const f32x4*)(AmV + (16 * rb + 2 * q + 1) * 68 + 4 * j4);
;                     f32x2v acc2 = sp[q];
;                     acc2 -= (f32x2v){a4[0], b4[0]} * T0; acc2 -= (f32x2v){a4[1], b4[1]} * T1; acc2 -= (f32x2v){a4[2], b4[2]} * T2; acc2 -= (f32x2v){a4[3], b4[3]} * T3;
;                     sp[q] = acc2; }
;             }
.LBB0_411:
	v_add_u32_e32 v40, 0x19800, v23
	ds_read_b32 v32, v40
	ds_read_b32 v34, v40 offset:272
	ds_read_b32 v36, v40 offset:544
	ds_read_b32 v38, v40 offset:816
	v_add_u32_e32 v41, 0x19800, v22
	ds_read_b128 v[182:185], v41
	ds_read_b128 v[186:189], v41 offset:272
	ds_read_b128 v[190:193], v41 offset:544
	ds_read_b128 v[194:197], v41 offset:816
	ds_read_b128 v[198:201], v41 offset:1088
	ds_read_b128 v[202:205], v41 offset:1360
	ds_read_b128 v[206:209], v41 offset:1632
	ds_read_b128 v[228:231], v41 offset:1904
	ds_read_b128 v[232:235], v41 offset:2176
	ds_read_b128 v[236:239], v41 offset:2448
	ds_read_b128 v[240:243], v41 offset:2720
	ds_read_b128 v[244:247], v41 offset:2992
	ds_read_b128 v[248:251], v41 offset:3264
	ds_read_b128 v[166:169], v41 offset:3536
	ds_read_b128 v[24:27], v41 offset:3808
	ds_read_b128 v[28:31], v41 offset:4080
	s_add_i32 s3, s3, -1
	v_add_u32_e32 v23, 0x440, v23
	v_add_u32_e32 v22, 16, v22
	s_waitcnt lgkmcnt(14)
	v_fma_f32 v86, -v32, v182, v86
	v_fma_f32 v87, -v32, v186, v87
	v_fma_f32 v86, -v34, v183, v86
	v_fma_f32 v87, -v34, v187, v87
	v_fma_f32 v86, -v36, v184, v86
	v_fma_f32 v87, -v36, v188, v87
	v_fma_f32 v86, -v38, v185, v86
	v_fma_f32 v87, -v38, v189, v87
	s_waitcnt lgkmcnt(12)
	v_fma_f32 v84, -v32, v190, v84
	v_fma_f32 v85, -v32, v194, v85
	v_fma_f32 v84, -v34, v191, v84
	v_fma_f32 v85, -v34, v195, v85
	v_fma_f32 v84, -v36, v192, v84
	v_fma_f32 v85, -v36, v196, v85
	v_fma_f32 v84, -v38, v193, v84
	v_fma_f32 v85, -v38, v197, v85
	s_waitcnt lgkmcnt(10)
	v_fma_f32 v80, -v32, v198, v80
	v_fma_f32 v81, -v32, v202, v81
	v_fma_f32 v80, -v34, v199, v80
	v_fma_f32 v81, -v34, v203, v81
	v_fma_f32 v80, -v36, v200, v80
	v_fma_f32 v81, -v36, v204, v81
	v_fma_f32 v80, -v38, v201, v80
	v_fma_f32 v81, -v38, v205, v81
	s_waitcnt lgkmcnt(8)
	v_fma_f32 v82, -v32, v206, v82
	v_fma_f32 v83, -v32, v228, v83
	v_fma_f32 v82, -v34, v207, v82
	v_fma_f32 v83, -v34, v229, v83
	v_fma_f32 v82, -v36, v208, v82
	v_fma_f32 v83, -v36, v230, v83
	v_fma_f32 v82, -v38, v209, v82
	v_fma_f32 v83, -v38, v231, v83
	s_waitcnt lgkmcnt(6)
	v_fma_f32 v78, -v32, v232, v78
	v_fma_f32 v79, -v32, v236, v79
	v_fma_f32 v78, -v34, v233, v78
	v_fma_f32 v79, -v34, v237, v79
	v_fma_f32 v78, -v36, v234, v78
	v_fma_f32 v79, -v36, v238, v79
	v_fma_f32 v78, -v38, v235, v78
	v_fma_f32 v79, -v38, v239, v79
	s_waitcnt lgkmcnt(4)
	v_fma_f32 v14, -v32, v240, v14
	v_fma_f32 v15, -v32, v244, v15
	v_fma_f32 v14, -v34, v241, v14
	v_fma_f32 v15, -v34, v245, v15
	v_fma_f32 v14, -v36, v242, v14
	v_fma_f32 v15, -v36, v246, v15
	v_fma_f32 v14, -v38, v243, v14
	v_fma_f32 v15, -v38, v247, v15
	s_waitcnt lgkmcnt(2)
	v_fma_f32 v76, -v32, v248, v76
	v_fma_f32 v77, -v32, v166, v77
	v_fma_f32 v76, -v34, v249, v76
	v_fma_f32 v77, -v34, v167, v77
	v_fma_f32 v76, -v36, v250, v76
	v_fma_f32 v77, -v36, v168, v77
	v_fma_f32 v76, -v38, v251, v76
	v_fma_f32 v77, -v38, v169, v77
	s_waitcnt lgkmcnt(0)
	v_fma_f32 v6, -v32, v24, v6
	v_fma_f32 v7, -v32, v28, v7
	v_fma_f32 v6, -v34, v25, v6
	v_fma_f32 v7, -v34, v29, v7
	v_fma_f32 v6, -v36, v26, v6
	v_fma_f32 v7, -v36, v30, v7
	v_fma_f32 v6, -v38, v27, v6
	v_fma_f32 v7, -v38, v31, v7
	s_cmp_eq_u32 s3, 0
	s_cbranch_scc0 .LBB0_411
	s_mul_i32 s19, s2, 0x110
	s_add_i32 s18, s19, 0x220
	s_add_i32 s17, s19, 0x440
	s_add_i32 s16, s19, 0x660
	s_add_i32 s15, s19, 0x880
	s_add_i32 s14, s19, 0xaa0
	s_add_i32 s11, s19, 0xcc0
	v_mov_b64_e32 v[88:89], v[86:87]
	v_mov_b64_e32 v[104:105], v[14:15]
	v_mov_b64_e32 v[102:103], v[6:7]
	s_mov_b32 s2, s9
	s_branch .LBB0_408
